# speedup vs baseline: 1.0106x; 1.0106x over previous
; __device__ __forceinline__ bf16x8 hy_afrag(const bf16_t* gbase, const bool t2, const bool t1, const unsigned sh) {
;   const uint4 lo = *(const uint4*)gbase, hi = *(const uint4*)(gbase + 8);
;   const unsigned x0 = t2 ? lo.z : lo.x, x1 = t2 ? lo.w : lo.y, x2 = t2 ? hi.x : lo.z, x3 = t2 ? hi.y : lo.w,
;                  x4 = t2 ? hi.z : hi.x, x5 = t2 ? hi.w : hi.y;
;   const unsigned y0 = t1 ? x1 : x0, y1 = t1 ? x2 : x1, y2 = t1 ? x3 : x2, y3 = t1 ? x4 : x3, y4 = t1 ? x5 : x4;
;   union { unsigned u[4]; bf16x8 v; } o;
;   o.u[0] = __builtin_amdgcn_alignbit(y1, y0, sh);
;   o.u[1] = __builtin_amdgcn_alignbit(y2, y1, sh);
;   o.u[2] = __builtin_amdgcn_alignbit(y3, y2, sh);
;   o.u[3] = __builtin_amdgcn_alignbit(y4, y3, sh);
;   return o.v;
; }
; template <int LSEL>
; __device__ __forceinline__ void hy_conv(const bf16_t* Z, const bf16_t* G, f32x4 (&acc)[4][4], int w, int lane) {
;     ...
;   for (int d = i_lo - (NB - 1); d <= i_hi; ++d) {
;     bf16x8 bf[4][2];
; #pragma unroll
;     for (int k = 0; k < 4; ++k) {
;       int js = (q0 + k) * BPT - d;
;       js = min(max(js, LSEL ? -1 : 0), NB - 1);
;       const bf16_t* bp = Z + zb + 64 * js;
;       bf[k][0] = *(const bf16x8*)bp;
;       bf[k][1] = *(const bf16x8*)(bp + 32);
;     }
;     const bf16_t* gb = G + (L - 64 * d + 8 * quad - r - s);
;     bf16x8 F[6];
; #pragma unroll
;     for (int u = 0; u < 6; ++u) F[u] = hy_afrag(gb + 16 * (u - 3), t2, t1, sh);
; #pragma unroll
;     for (int k = 0; k < 4; ++k) {
;       const int js = (q0 + k) * BPT - d;
;       const bool valid = LSEL ? (js >= -1 && js <= NB - 1) : (js >= 0 && js <= NB - 1);
;       if (valid) {
; #pragma unroll
;         for (int mt = 0; mt < 4; ++mt) {
;           acc[k][mt] = __builtin_amdgcn_mfma_f32_16x16x32_bf16(F[3 - mt], bf[k][0], acc[k][mt], 0, 0, 0);
;           acc[k][mt] = __builtin_amdgcn_mfma_f32_16x16x32_bf16(F[5 - mt], bf[k][1], acc[k][mt], 0, 0, 0);
;         }
;       }
;     }
;   }
.LBB0_835:
	v_add_u32_e32 v0, s9, v176
	v_mov_b32_e32 v140, v108
	v_mov_b32_e32 v141, v109
	v_mov_b32_e32 v142, v110
	v_mov_b32_e32 v143, v111
	v_mov_b32_e32 v144, v120
	v_mov_b32_e32 v145, v121
	v_mov_b32_e32 v146, v122
	v_mov_b32_e32 v147, v123
	ds_read2_b32 v[108:109], v0 offset1:1
	ds_read2_b32 v[110:111], v0 offset0:2 offset1:3
	ds_read_b32 v2, v0 offset:16
	ds_read2_b32 v[120:121], v0 offset0:8 offset1:9
	ds_read2_b32 v[122:123], v0 offset0:10 offset1:11
	ds_read_b32 v3, v0 offset:48
	ds_read2_b32 v[124:125], v0 offset0:16 offset1:17
	ds_read2_b32 v[126:127], v0 offset0:18 offset1:19
	ds_read_b32 v177, v0 offset:80
	ds_read2_b32 v[136:137], v0 offset0:24 offset1:25
	ds_read2_b32 v[138:139], v0 offset0:26 offset1:27
	ds_read_b32 v178, v0 offset:112
	s_add_i32 s12, s8, 1
	v_med3_i32 v0, s12, 0, 31
	v_lshl_add_u32 v0, v0, 7, v153
	s_add_i32 s11, s8, 2
	ds_read_b128 v[128:131], v0
	ds_read_b128 v[132:135], v0 offset:64
	s_waitcnt lgkmcnt(11)
	v_alignbit_b32 v108, v109, v108, v152
	v_alignbit_b32 v109, v110, v109, v152
	v_alignbit_b32 v110, v111, v110, v152
	v_alignbit_b32 v111, v2, v111, v152
	v_med3_i32 v0, s11, 0, 31
	s_add_i32 s10, s8, 3
	v_lshl_add_u32 v0, v0, 7, v153
	s_min_u32 s13, s10, 31
	ds_read_b128 v[112:115], v0
	ds_read_b128 v[116:119], v0 offset:64
	s_waitcnt lgkmcnt(10)
	v_alignbit_b32 v120, v121, v120, v152
	v_alignbit_b32 v121, v122, v121, v152
	v_alignbit_b32 v122, v123, v122, v152
	v_alignbit_b32 v123, v3, v123, v152
	v_lshl_add_u32 v0, s13, 7, v153
	ds_read_b128 v[100:103], v0
	ds_read_b128 v[104:107], v0 offset:64
	s_waitcnt lgkmcnt(9)
	v_alignbit_b32 v124, v125, v124, v152
	v_alignbit_b32 v125, v126, v125, v152
	v_alignbit_b32 v126, v127, v126, v152
	v_alignbit_b32 v127, v177, v127, v152
	s_waitcnt lgkmcnt(6)
	v_alignbit_b32 v136, v137, v136, v152
	v_alignbit_b32 v137, v138, v137, v152
	v_alignbit_b32 v138, v139, v138, v152
	v_alignbit_b32 v139, v178, v139, v152
	s_waitcnt lgkmcnt(0)
	s_cmp_lt_u32 s8, 29
	s_cbranch_scc0 .Lhy_slow_835
	v_add_u32_e32 v0, s9, v154
	ds_read_b128 v[166:169], v0
	ds_read_b128 v[170:173], v0 offset:64
	s_setprio 1
	v_mfma_f32_16x16x32_bf16 v[64:67], v[136:139], v[112:115], v[64:67]
	v_mfma_f32_16x16x32_bf16 v[60:63], v[124:127], v[112:115], v[60:63]
	v_mfma_f32_16x16x32_bf16 v[56:59], v[120:123], v[112:115], v[56:59]
	v_mfma_f32_16x16x32_bf16 v[52:55], v[108:111], v[112:115], v[52:55]
	v_mfma_f32_16x16x32_bf16 v[64:67], v[144:147], v[116:119], v[64:67]
	v_mfma_f32_16x16x32_bf16 v[60:63], v[140:143], v[116:119], v[60:63]
	v_mfma_f32_16x16x32_bf16 v[56:59], v[136:139], v[116:119], v[56:59]
	v_mfma_f32_16x16x32_bf16 v[52:55], v[124:127], v[116:119], v[52:55]
	v_mfma_f32_16x16x32_bf16 v[80:83], v[136:139], v[128:131], v[80:83]
	v_mfma_f32_16x16x32_bf16 v[76:79], v[124:127], v[128:131], v[76:79]
	v_mfma_f32_16x16x32_bf16 v[72:75], v[120:123], v[128:131], v[72:75]
	v_mfma_f32_16x16x32_bf16 v[68:71], v[108:111], v[128:131], v[68:71]
	v_mfma_f32_16x16x32_bf16 v[80:83], v[144:147], v[132:135], v[80:83]
	v_mfma_f32_16x16x32_bf16 v[76:79], v[140:143], v[132:135], v[76:79]
	v_mfma_f32_16x16x32_bf16 v[72:75], v[136:139], v[132:135], v[72:75]
	v_mfma_f32_16x16x32_bf16 v[68:71], v[124:127], v[132:135], v[68:71]
	v_mfma_f32_16x16x32_bf16 v[48:51], v[136:139], v[100:103], v[48:51]
	v_mfma_f32_16x16x32_bf16 v[44:47], v[124:127], v[100:103], v[44:47]
	v_mfma_f32_16x16x32_bf16 v[40:43], v[120:123], v[100:103], v[40:43]
	v_mfma_f32_16x16x32_bf16 v[36:39], v[108:111], v[100:103], v[36:39]
	v_mfma_f32_16x16x32_bf16 v[48:51], v[144:147], v[104:107], v[48:51]
	v_mfma_f32_16x16x32_bf16 v[44:47], v[140:143], v[104:107], v[44:47]
	v_mfma_f32_16x16x32_bf16 v[40:43], v[136:139], v[104:107], v[40:43]
	v_mfma_f32_16x16x32_bf16 v[36:39], v[124:127], v[104:107], v[36:39]
	s_setprio 0
	s_waitcnt lgkmcnt(0)
	s_setprio 1
	v_mfma_f32_16x16x32_bf16 v[96:99], v[136:139], v[166:169], v[96:99]
	v_mfma_f32_16x16x32_bf16 v[92:95], v[124:127], v[166:169], v[92:95]
	v_mfma_f32_16x16x32_bf16 v[88:91], v[120:123], v[166:169], v[88:91]
	v_mfma_f32_16x16x32_bf16 v[84:87], v[108:111], v[166:169], v[84:87]
	v_mfma_f32_16x16x32_bf16 v[96:99], v[144:147], v[170:173], v[96:99]
	v_mfma_f32_16x16x32_bf16 v[92:95], v[140:143], v[170:173], v[92:95]
	v_mfma_f32_16x16x32_bf16 v[88:91], v[136:139], v[170:173], v[88:91]
	v_mfma_f32_16x16x32_bf16 v[84:87], v[124:127], v[170:173], v[84:87]
	s_setprio 0
	s_addk_i32 s9, 0xff80
	s_add_i32 s8, s8, -1
	s_cmpk_lg_i32 s9, 0xee80
	s_cbranch_scc1 .LBB0_835
	s_branch .LBB0_843
.Lhy_slow_835:
	s_cmp_gt_u32 s8, 31
	s_cbranch_scc1 .LBB0_839
	v_add_u32_e32 v0, s9, v154
	ds_read_b128 v[166:169], v0
	ds_read_b128 v[170:173], v0 offset:64
	s_waitcnt lgkmcnt(1)
	s_setprio 1
	v_mfma_f32_16x16x32_bf16 v[96:99], v[136:139], v[166:169], v[96:99]
	v_mfma_f32_16x16x32_bf16 v[92:95], v[124:127], v[166:169], v[92:95]
	v_mfma_f32_16x16x32_bf16 v[88:91], v[120:123], v[166:169], v[88:91]
	v_mfma_f32_16x16x32_bf16 v[84:87], v[108:111], v[166:169], v[84:87]
	s_setprio 0
	s_waitcnt lgkmcnt(0)
	s_setprio 1
	v_mfma_f32_16x16x32_bf16 v[96:99], v[144:147], v[170:173], v[96:99]
	v_mfma_f32_16x16x32_bf16 v[92:95], v[140:143], v[170:173], v[92:95]
	v_mfma_f32_16x16x32_bf16 v[88:91], v[136:139], v[170:173], v[88:91]
	v_mfma_f32_16x16x32_bf16 v[84:87], v[124:127], v[170:173], v[84:87]
	s_setprio 0
	s_cmp_gt_u32 s12, 31
	s_cbranch_scc0 .LBB0_840

; template <int LSEL>
; __device__ __forceinline__ void hy_conv(const bf16_t* Z, const bf16_t* G, f32x4 (&acc)[4][4], int w, int lane) {
;     ...
; #pragma unroll
;     for (int k = 0; k < 4; ++k) {
;       const int js = (q0 + k) * BPT - d;
;       const bool valid = LSEL ? (js >= -1 && js <= NB - 1) : (js >= 0 && js <= NB - 1);
;       if (valid) {
; #pragma unroll
;         for (int mt = 0; mt < 4; ++mt) {
;           acc[k][mt] = __builtin_amdgcn_mfma_f32_16x16x32_bf16(F[3 - mt], bf[k][0], acc[k][mt], 0, 0, 0);
;           acc[k][mt] = __builtin_amdgcn_mfma_f32_16x16x32_bf16(F[5 - mt], bf[k][1], acc[k][mt], 0, 0, 0);
;         }
;       }
;     }
.LBB0_838:
	s_setprio 1
	v_mfma_f32_16x16x32_bf16 v[64:67], v[136:139], v[112:115], v[64:67]
	v_mfma_f32_16x16x32_bf16 v[60:63], v[124:127], v[112:115], v[60:63]
	v_mfma_f32_16x16x32_bf16 v[56:59], v[120:123], v[112:115], v[56:59]
	v_mfma_f32_16x16x32_bf16 v[52:55], v[108:111], v[112:115], v[52:55]
	v_mfma_f32_16x16x32_bf16 v[64:67], v[144:147], v[116:119], v[64:67]
	v_mfma_f32_16x16x32_bf16 v[60:63], v[140:143], v[116:119], v[60:63]
	v_mfma_f32_16x16x32_bf16 v[56:59], v[136:139], v[116:119], v[56:59]
	v_mfma_f32_16x16x32_bf16 v[52:55], v[124:127], v[116:119], v[52:55]
	s_setprio 0
	s_cmp_gt_u32 s10, 31
	s_cbranch_scc1 .LBB0_834
	s_branch .LBB0_842

; template <int LSEL>
; __device__ __forceinline__ void hy_conv(const bf16_t* Z, const bf16_t* G, f32x4 (&acc)[4][4], int w, int lane) {
;     ...
; #pragma unroll
;     for (int k = 0; k < 4; ++k) {
;       const int js = (q0 + k) * BPT - d;
;       const bool valid = LSEL ? (js >= -1 && js <= NB - 1) : (js >= 0 && js <= NB - 1);
;       if (valid) {
; #pragma unroll
;         for (int mt = 0; mt < 4; ++mt) {
;           acc[k][mt] = __builtin_amdgcn_mfma_f32_16x16x32_bf16(F[3 - mt], bf[k][0], acc[k][mt], 0, 0, 0);
;           acc[k][mt] = __builtin_amdgcn_mfma_f32_16x16x32_bf16(F[5 - mt], bf[k][1], acc[k][mt], 0, 0, 0);
;         }
;       }
;     }
.LBB0_840:
	s_setprio 1
	v_mfma_f32_16x16x32_bf16 v[80:83], v[136:139], v[128:131], v[80:83]
	v_mfma_f32_16x16x32_bf16 v[76:79], v[124:127], v[128:131], v[76:79]
	v_mfma_f32_16x16x32_bf16 v[72:75], v[120:123], v[128:131], v[72:75]
	v_mfma_f32_16x16x32_bf16 v[68:71], v[108:111], v[128:131], v[68:71]
	v_mfma_f32_16x16x32_bf16 v[80:83], v[144:147], v[132:135], v[80:83]
	v_mfma_f32_16x16x32_bf16 v[76:79], v[140:143], v[132:135], v[76:79]
	v_mfma_f32_16x16x32_bf16 v[72:75], v[136:139], v[132:135], v[72:75]
	v_mfma_f32_16x16x32_bf16 v[68:71], v[124:127], v[132:135], v[68:71]
	s_setprio 0
	s_cmp_gt_u32 s11, 31
	s_cbranch_scc0 .LBB0_838

; template <int LSEL>
; __device__ __forceinline__ void hy_conv(const bf16_t* Z, const bf16_t* G, f32x4 (&acc)[4][4], int w, int lane) {
;     ...
; #pragma unroll
;     for (int k = 0; k < 4; ++k) {
;       const int js = (q0 + k) * BPT - d;
;       const bool valid = LSEL ? (js >= -1 && js <= NB - 1) : (js >= 0 && js <= NB - 1);
;       if (valid) {
; #pragma unroll
;         for (int mt = 0; mt < 4; ++mt) {
;           acc[k][mt] = __builtin_amdgcn_mfma_f32_16x16x32_bf16(F[3 - mt], bf[k][0], acc[k][mt], 0, 0, 0);
;           acc[k][mt] = __builtin_amdgcn_mfma_f32_16x16x32_bf16(F[5 - mt], bf[k][1], acc[k][mt], 0, 0, 0);
;         }
;       }
;     }
.LBB0_842:
	s_setprio 1
	v_mfma_f32_16x16x32_bf16 v[48:51], v[136:139], v[100:103], v[48:51]
	v_mfma_f32_16x16x32_bf16 v[44:47], v[124:127], v[100:103], v[44:47]
	v_mfma_f32_16x16x32_bf16 v[40:43], v[120:123], v[100:103], v[40:43]
	v_mfma_f32_16x16x32_bf16 v[36:39], v[108:111], v[100:103], v[36:39]
	v_mfma_f32_16x16x32_bf16 v[48:51], v[144:147], v[104:107], v[48:51]
	v_mfma_f32_16x16x32_bf16 v[44:47], v[140:143], v[104:107], v[44:47]
	v_mfma_f32_16x16x32_bf16 v[40:43], v[136:139], v[104:107], v[40:43]
	v_mfma_f32_16x16x32_bf16 v[36:39], v[124:127], v[104:107], v[36:39]
	s_setprio 0
	s_branch .LBB0_834

; __device__ __forceinline__ bf16x8 hy_afrag(const bf16_t* gbase, const bool t2, const bool t1, const unsigned sh) {
;   const uint4 lo = *(const uint4*)gbase, hi = *(const uint4*)(gbase + 8);
;   const unsigned x0 = t2 ? lo.z : lo.x, x1 = t2 ? lo.w : lo.y, x2 = t2 ? hi.x : lo.z, x3 = t2 ? hi.y : lo.w,
;                  x4 = t2 ? hi.z : hi.x, x5 = t2 ? hi.w : hi.y;
;   const unsigned y0 = t1 ? x1 : x0, y1 = t1 ? x2 : x1, y2 = t1 ? x3 : x2, y3 = t1 ? x4 : x3, y4 = t1 ? x5 : x4;
;   union { unsigned u[4]; bf16x8 v; } o;
;   o.u[0] = __builtin_amdgcn_alignbit(y1, y0, sh);
;   o.u[1] = __builtin_amdgcn_alignbit(y2, y1, sh);
;   o.u[2] = __builtin_amdgcn_alignbit(y3, y2, sh);
;   o.u[3] = __builtin_amdgcn_alignbit(y4, y3, sh);
;   return o.v;
; }
; template <int LSEL>
; __device__ __forceinline__ void hy_conv(const bf16_t* Z, const bf16_t* G, f32x4 (&acc)[4][4], int w, int lane) {
;     ...
;   for (int d = i_lo - (NB - 1); d <= i_hi; ++d) {
;     bf16x8 bf[4][2];
; #pragma unroll
;     for (int k = 0; k < 4; ++k) {
;       int js = (q0 + k) * BPT - d;
;       js = min(max(js, LSEL ? -1 : 0), NB - 1);
;       const bf16_t* bp = Z + zb + 64 * js;
;       bf[k][0] = *(const bf16x8*)bp;
;       bf[k][1] = *(const bf16x8*)(bp + 32);
;     }
;     const bf16_t* gb = G + (L - 64 * d + 8 * quad - r - s);
;     bf16x8 F[6];
; #pragma unroll
;     for (int u = 0; u < 6; ++u) F[u] = hy_afrag(gb + 16 * (u - 3), t2, t1, sh);
; #pragma unroll
;     for (int k = 0; k < 4; ++k) {
;       const int js = (q0 + k) * BPT - d;
;       const bool valid = LSEL ? (js >= -1 && js <= NB - 1) : (js >= 0 && js <= NB - 1);
;       if (valid) {
; #pragma unroll
;         for (int mt = 0; mt < 4; ++mt) {
;           acc[k][mt] = __builtin_amdgcn_mfma_f32_16x16x32_bf16(F[3 - mt], bf[k][0], acc[k][mt], 0, 0, 0);
;           acc[k][mt] = __builtin_amdgcn_mfma_f32_16x16x32_bf16(F[5 - mt], bf[k][1], acc[k][mt], 0, 0, 0);
;         }
;       }
;     }
;   }
.LBB0_928:
	v_add_u32_e32 v0, s8, v176
	v_mov_b32_e32 v140, v108
	v_mov_b32_e32 v141, v109
	v_mov_b32_e32 v142, v110
	v_mov_b32_e32 v143, v111
	v_mov_b32_e32 v144, v120
	v_mov_b32_e32 v145, v121
	v_mov_b32_e32 v146, v122
	v_mov_b32_e32 v147, v123
	ds_read2_b32 v[108:109], v0 offset1:1
	ds_read2_b32 v[110:111], v0 offset0:2 offset1:3
	ds_read_b32 v2, v0 offset:16
	ds_read2_b32 v[120:121], v0 offset0:8 offset1:9
	ds_read2_b32 v[122:123], v0 offset0:10 offset1:11
	ds_read_b32 v3, v0 offset:48
	ds_read2_b32 v[124:125], v0 offset0:16 offset1:17
	ds_read2_b32 v[126:127], v0 offset0:18 offset1:19
	ds_read_b32 v177, v0 offset:80
	ds_read2_b32 v[136:137], v0 offset0:24 offset1:25
	ds_read2_b32 v[138:139], v0 offset0:26 offset1:27
	ds_read_b32 v178, v0 offset:112
	s_add_i32 s12, s9, 1
	v_med3_i32 v0, s12, 0, 31
	v_lshl_add_u32 v0, v0, 7, v153
	s_add_i32 s11, s9, 2
	ds_read_b128 v[128:131], v0
	ds_read_b128 v[132:135], v0 offset:64
	s_waitcnt lgkmcnt(11)
	v_alignbit_b32 v108, v109, v108, v152
	v_alignbit_b32 v109, v110, v109, v152
	v_alignbit_b32 v110, v111, v110, v152
	v_alignbit_b32 v111, v2, v111, v152
	v_med3_i32 v0, s11, 0, 31
	s_add_i32 s10, s9, 3
	v_lshl_add_u32 v0, v0, 7, v153
	s_min_u32 s13, s10, 31
	ds_read_b128 v[112:115], v0
	ds_read_b128 v[116:119], v0 offset:64
	s_waitcnt lgkmcnt(10)
	v_alignbit_b32 v120, v121, v120, v152
	v_alignbit_b32 v121, v122, v121, v152
	v_alignbit_b32 v122, v123, v122, v152
	v_alignbit_b32 v123, v3, v123, v152
	v_lshl_add_u32 v0, s13, 7, v153
	ds_read_b128 v[100:103], v0
	ds_read_b128 v[104:107], v0 offset:64
	s_waitcnt lgkmcnt(9)
	v_alignbit_b32 v124, v125, v124, v152
	v_alignbit_b32 v125, v126, v125, v152
	v_alignbit_b32 v126, v127, v126, v152
	v_alignbit_b32 v127, v177, v127, v152
	s_waitcnt lgkmcnt(6)
	v_alignbit_b32 v136, v137, v136, v152
	v_alignbit_b32 v137, v138, v137, v152
	v_alignbit_b32 v138, v139, v138, v152
	v_alignbit_b32 v139, v178, v139, v152
	s_waitcnt lgkmcnt(0)
	s_cmp_lt_u32 s9, 29
	s_cbranch_scc0 .Lhy_slow_928
	v_add_u32_e32 v0, s8, v154
	ds_read_b128 v[166:169], v0
	ds_read_b128 v[170:173], v0 offset:64
	s_setprio 1
	v_mfma_f32_16x16x32_bf16 v[36:39], v[136:139], v[112:115], v[36:39]
	v_mfma_f32_16x16x32_bf16 v[32:35], v[124:127], v[112:115], v[32:35]
	v_mfma_f32_16x16x32_bf16 v[28:31], v[120:123], v[112:115], v[28:31]
	v_mfma_f32_16x16x32_bf16 v[24:27], v[108:111], v[112:115], v[24:27]
	v_mfma_f32_16x16x32_bf16 v[36:39], v[144:147], v[116:119], v[36:39]
	v_mfma_f32_16x16x32_bf16 v[32:35], v[140:143], v[116:119], v[32:35]
	v_mfma_f32_16x16x32_bf16 v[28:31], v[136:139], v[116:119], v[28:31]
	v_mfma_f32_16x16x32_bf16 v[24:27], v[124:127], v[116:119], v[24:27]
	v_mfma_f32_16x16x32_bf16 v[56:59], v[136:139], v[128:131], v[56:59]
	v_mfma_f32_16x16x32_bf16 v[52:55], v[124:127], v[128:131], v[52:55]
	v_mfma_f32_16x16x32_bf16 v[48:51], v[120:123], v[128:131], v[48:51]
	v_mfma_f32_16x16x32_bf16 v[40:43], v[108:111], v[128:131], v[40:43]
	v_mfma_f32_16x16x32_bf16 v[56:59], v[144:147], v[132:135], v[56:59]
	v_mfma_f32_16x16x32_bf16 v[52:55], v[140:143], v[132:135], v[52:55]
	v_mfma_f32_16x16x32_bf16 v[48:51], v[136:139], v[132:135], v[48:51]
	v_mfma_f32_16x16x32_bf16 v[40:43], v[124:127], v[132:135], v[40:43]
	v_mfma_f32_16x16x32_bf16 v[20:23], v[136:139], v[100:103], v[20:23]
	v_mfma_f32_16x16x32_bf16 v[12:15], v[124:127], v[100:103], v[12:15]
	v_mfma_f32_16x16x32_bf16 v[8:11], v[120:123], v[100:103], v[8:11]
	v_mfma_f32_16x16x32_bf16 v[2:5], v[108:111], v[100:103], v[4:7]
	v_mfma_f32_16x16x32_bf16 v[20:23], v[144:147], v[104:107], v[20:23]
	v_mfma_f32_16x16x32_bf16 v[12:15], v[140:143], v[104:107], v[12:15]
	v_mfma_f32_16x16x32_bf16 v[8:11], v[136:139], v[104:107], v[8:11]
	v_mfma_f32_16x16x32_bf16 v[4:7], v[124:127], v[104:107], v[2:5]
	s_setprio 0
	s_waitcnt lgkmcnt(0)
	s_setprio 1
	v_mfma_f32_16x16x32_bf16 v[76:79], v[136:139], v[166:169], v[76:79]
	v_mfma_f32_16x16x32_bf16 v[68:71], v[124:127], v[166:169], v[68:71]
	v_mfma_f32_16x16x32_bf16 v[64:67], v[120:123], v[166:169], v[64:67]
	v_mfma_f32_16x16x32_bf16 v[60:63], v[108:111], v[166:169], v[60:63]
	v_mfma_f32_16x16x32_bf16 v[76:79], v[144:147], v[170:173], v[76:79]
	v_mfma_f32_16x16x32_bf16 v[68:71], v[140:143], v[170:173], v[68:71]
	v_mfma_f32_16x16x32_bf16 v[64:67], v[136:139], v[170:173], v[64:67]
	v_mfma_f32_16x16x32_bf16 v[60:63], v[124:127], v[170:173], v[60:63]
	s_setprio 0
	s_addk_i32 s8, 0xff80
	s_add_i32 s9, s9, -1
	s_cmpk_lg_i32 s8, 0xee80
	s_cbranch_scc1 .LBB0_928
	s_branch .LBB0_936
.Lhy_slow_928:
	s_cmp_gt_u32 s9, 31
	s_cbranch_scc1 .LBB0_932
	v_add_u32_e32 v0, s8, v154
	ds_read_b128 v[166:169], v0
	ds_read_b128 v[170:173], v0 offset:64
	s_waitcnt lgkmcnt(1)
	s_setprio 1
	v_mfma_f32_16x16x32_bf16 v[76:79], v[136:139], v[166:169], v[76:79]
	v_mfma_f32_16x16x32_bf16 v[68:71], v[124:127], v[166:169], v[68:71]
	v_mfma_f32_16x16x32_bf16 v[64:67], v[120:123], v[166:169], v[64:67]
	v_mfma_f32_16x16x32_bf16 v[60:63], v[108:111], v[166:169], v[60:63]
	s_setprio 0
	s_waitcnt lgkmcnt(0)
	s_setprio 1
	v_mfma_f32_16x16x32_bf16 v[76:79], v[144:147], v[170:173], v[76:79]
	v_mfma_f32_16x16x32_bf16 v[68:71], v[140:143], v[170:173], v[68:71]
	v_mfma_f32_16x16x32_bf16 v[64:67], v[136:139], v[170:173], v[64:67]
	v_mfma_f32_16x16x32_bf16 v[60:63], v[124:127], v[170:173], v[60:63]
	s_setprio 0
	s_cmp_gt_u32 s12, 31
	s_cbranch_scc0 .LBB0_933

; template <int LSEL>
; __device__ __forceinline__ void hy_conv(const bf16_t* Z, const bf16_t* G, f32x4 (&acc)[4][4], int w, int lane) {
;     ...
; #pragma unroll
;     for (int k = 0; k < 4; ++k) {
;       const int js = (q0 + k) * BPT - d;
;       const bool valid = LSEL ? (js >= -1 && js <= NB - 1) : (js >= 0 && js <= NB - 1);
;       if (valid) {
; #pragma unroll
;         for (int mt = 0; mt < 4; ++mt) {
;           acc[k][mt] = __builtin_amdgcn_mfma_f32_16x16x32_bf16(F[3 - mt], bf[k][0], acc[k][mt], 0, 0, 0);
;           acc[k][mt] = __builtin_amdgcn_mfma_f32_16x16x32_bf16(F[5 - mt], bf[k][1], acc[k][mt], 0, 0, 0);
;         }
;       }
;     }
.LBB0_931:
	s_setprio 1
	v_mfma_f32_16x16x32_bf16 v[36:39], v[136:139], v[112:115], v[36:39]
	v_mfma_f32_16x16x32_bf16 v[32:35], v[124:127], v[112:115], v[32:35]
	v_mfma_f32_16x16x32_bf16 v[28:31], v[120:123], v[112:115], v[28:31]
	v_mfma_f32_16x16x32_bf16 v[24:27], v[108:111], v[112:115], v[24:27]
	v_mfma_f32_16x16x32_bf16 v[36:39], v[144:147], v[116:119], v[36:39]
	v_mfma_f32_16x16x32_bf16 v[32:35], v[140:143], v[116:119], v[32:35]
	v_mfma_f32_16x16x32_bf16 v[28:31], v[136:139], v[116:119], v[28:31]
	v_mfma_f32_16x16x32_bf16 v[24:27], v[124:127], v[116:119], v[24:27]
	s_setprio 0
	s_cmp_gt_u32 s10, 31
	s_cbranch_scc1 .LBB0_927
	s_branch .LBB0_935

; template <int LSEL>
; __device__ __forceinline__ void hy_conv(const bf16_t* Z, const bf16_t* G, f32x4 (&acc)[4][4], int w, int lane) {
;     ...
; #pragma unroll
;     for (int k = 0; k < 4; ++k) {
;       const int js = (q0 + k) * BPT - d;
;       const bool valid = LSEL ? (js >= -1 && js <= NB - 1) : (js >= 0 && js <= NB - 1);
;       if (valid) {
; #pragma unroll
;         for (int mt = 0; mt < 4; ++mt) {
;           acc[k][mt] = __builtin_amdgcn_mfma_f32_16x16x32_bf16(F[3 - mt], bf[k][0], acc[k][mt], 0, 0, 0);
;           acc[k][mt] = __builtin_amdgcn_mfma_f32_16x16x32_bf16(F[5 - mt], bf[k][1], acc[k][mt], 0, 0, 0);
;         }
;       }
;     }
.LBB0_933:
	s_setprio 1
	v_mfma_f32_16x16x32_bf16 v[56:59], v[136:139], v[128:131], v[56:59]
	v_mfma_f32_16x16x32_bf16 v[52:55], v[124:127], v[128:131], v[52:55]
	v_mfma_f32_16x16x32_bf16 v[48:51], v[120:123], v[128:131], v[48:51]
	v_mfma_f32_16x16x32_bf16 v[40:43], v[108:111], v[128:131], v[40:43]
	v_mfma_f32_16x16x32_bf16 v[56:59], v[144:147], v[132:135], v[56:59]
	v_mfma_f32_16x16x32_bf16 v[52:55], v[140:143], v[132:135], v[52:55]
	v_mfma_f32_16x16x32_bf16 v[48:51], v[136:139], v[132:135], v[48:51]
	v_mfma_f32_16x16x32_bf16 v[40:43], v[124:127], v[132:135], v[40:43]
	s_setprio 0
	s_cmp_gt_u32 s11, 31
	s_cbranch_scc0 .LBB0_931

; template <int LSEL>
; __device__ __forceinline__ void hy_conv(const bf16_t* Z, const bf16_t* G, f32x4 (&acc)[4][4], int w, int lane) {
;     ...
; #pragma unroll
;     for (int k = 0; k < 4; ++k) {
;       const int js = (q0 + k) * BPT - d;
;       const bool valid = LSEL ? (js >= -1 && js <= NB - 1) : (js >= 0 && js <= NB - 1);
;       if (valid) {
; #pragma unroll
;         for (int mt = 0; mt < 4; ++mt) {
;           acc[k][mt] = __builtin_amdgcn_mfma_f32_16x16x32_bf16(F[3 - mt], bf[k][0], acc[k][mt], 0, 0, 0);
;           acc[k][mt] = __builtin_amdgcn_mfma_f32_16x16x32_bf16(F[5 - mt], bf[k][1], acc[k][mt], 0, 0, 0);
;         }
;       }
;     }
.LBB0_935:
	s_setprio 1
	v_mfma_f32_16x16x32_bf16 v[20:23], v[136:139], v[100:103], v[20:23]
	v_mfma_f32_16x16x32_bf16 v[12:15], v[124:127], v[100:103], v[12:15]
	v_mfma_f32_16x16x32_bf16 v[8:11], v[120:123], v[100:103], v[8:11]
	v_mfma_f32_16x16x32_bf16 v[2:5], v[108:111], v[100:103], v[4:7]
	v_mfma_f32_16x16x32_bf16 v[20:23], v[144:147], v[104:107], v[20:23]
	v_mfma_f32_16x16x32_bf16 v[12:15], v[140:143], v[104:107], v[12:15]
	v_mfma_f32_16x16x32_bf16 v[8:11], v[136:139], v[104:107], v[8:11]
	v_mfma_f32_16x16x32_bf16 v[4:7], v[124:127], v[104:107], v[2:5]
	s_setprio 0
	s_branch .LBB0_927

; __device__ __forceinline__ bf16x8 hy_afrag(const bf16_t* gbase, const bool t2, const bool t1, const unsigned sh) {
;   const uint4 lo = *(const uint4*)gbase, hi = *(const uint4*)(gbase + 8);
;   const unsigned x0 = t2 ? lo.z : lo.x, x1 = t2 ? lo.w : lo.y, x2 = t2 ? hi.x : lo.z, x3 = t2 ? hi.y : lo.w,
;                  x4 = t2 ? hi.z : hi.x, x5 = t2 ? hi.w : hi.y;
;   const unsigned y0 = t1 ? x1 : x0, y1 = t1 ? x2 : x1, y2 = t1 ? x3 : x2, y3 = t1 ? x4 : x3, y4 = t1 ? x5 : x4;
;   union { unsigned u[4]; bf16x8 v; } o;
;   o.u[0] = __builtin_amdgcn_alignbit(y1, y0, sh);
;   o.u[1] = __builtin_amdgcn_alignbit(y2, y1, sh);
;   o.u[2] = __builtin_amdgcn_alignbit(y3, y2, sh);
;   o.u[3] = __builtin_amdgcn_alignbit(y4, y3, sh);
;   return o.v;
; }
; template <int LSEL>
; __device__ __forceinline__ void hy_conv(const bf16_t* Z, const bf16_t* G, f32x4 (&acc)[4][4], int w, int lane) {
;     ...
;   for (int d = i_lo - (NB - 1); d <= i_hi; ++d) {
;     bf16x8 bf[4][2];
; #pragma unroll
;     for (int k = 0; k < 4; ++k) {
;       int js = (q0 + k) * BPT - d;
;       js = min(max(js, LSEL ? -1 : 0), NB - 1);
;       const bf16_t* bp = Z + zb + 64 * js;
;       bf[k][0] = *(const bf16x8*)bp;
;       bf[k][1] = *(const bf16x8*)(bp + 32);
;     }
;     const bf16_t* gb = G + (L - 64 * d + 8 * quad - r - s);
;     bf16x8 F[6];
; #pragma unroll
;     for (int u = 0; u < 6; ++u) F[u] = hy_afrag(gb + 16 * (u - 3), t2, t1, sh);
; #pragma unroll
;     for (int k = 0; k < 4; ++k) {
;       const int js = (q0 + k) * BPT - d;
;       const bool valid = LSEL ? (js >= -1 && js <= NB - 1) : (js >= 0 && js <= NB - 1);
;       if (valid) {
; #pragma unroll
;         for (int mt = 0; mt < 4; ++mt) {
;           acc[k][mt] = __builtin_amdgcn_mfma_f32_16x16x32_bf16(F[3 - mt], bf[k][0], acc[k][mt], 0, 0, 0);
;           acc[k][mt] = __builtin_amdgcn_mfma_f32_16x16x32_bf16(F[5 - mt], bf[k][1], acc[k][mt], 0, 0, 0);
;         }
;       }
;     }
;   }
.LBB0_1112:
	v_add_u32_e32 v0, s8, v176
	v_mov_b32_e32 v138, v106
	v_mov_b32_e32 v139, v107
	v_mov_b32_e32 v140, v108
	v_mov_b32_e32 v141, v109
	v_mov_b32_e32 v142, v118
	v_mov_b32_e32 v143, v119
	v_mov_b32_e32 v144, v120
	v_mov_b32_e32 v145, v121
	ds_read2_b32 v[106:107], v0 offset1:1
	ds_read2_b32 v[108:109], v0 offset0:2 offset1:3
	ds_read_b32 v2, v0 offset:16
	ds_read2_b32 v[118:119], v0 offset0:8 offset1:9
	ds_read2_b32 v[120:121], v0 offset0:10 offset1:11
	ds_read_b32 v3, v0 offset:48
	ds_read2_b32 v[122:123], v0 offset0:16 offset1:17
	ds_read2_b32 v[124:125], v0 offset0:18 offset1:19
	ds_read_b32 v177, v0 offset:80
	ds_read2_b32 v[134:135], v0 offset0:24 offset1:25
	ds_read2_b32 v[136:137], v0 offset0:26 offset1:27
	ds_read_b32 v178, v0 offset:112
	s_add_i32 s10, s9, 1
	v_med3_i32 v0, s10, -1, 63
	v_lshl_add_u32 v0, v0, 7, v154
	s_add_i32 s10, s9, 3
	ds_read_b128 v[126:129], v0 offset:128
	ds_read_b128 v[130:133], v0 offset:192
	s_waitcnt lgkmcnt(11)
	v_alignbit_b32 v106, v107, v106, v151
	v_alignbit_b32 v107, v108, v107, v151
	v_alignbit_b32 v108, v109, v108, v151
	v_alignbit_b32 v109, v2, v109, v151
	v_med3_i32 v0, s10, -1, 63
	s_add_i32 s10, s9, 5
	v_lshl_add_u32 v0, v0, 7, v154
	s_min_i32 s10, s10, 63
	ds_read_b128 v[110:113], v0 offset:128
	ds_read_b128 v[114:117], v0 offset:192
	s_waitcnt lgkmcnt(10)
	v_alignbit_b32 v118, v119, v118, v151
	v_alignbit_b32 v119, v120, v119, v151
	v_alignbit_b32 v120, v121, v120, v151
	v_alignbit_b32 v121, v3, v121, v151
	v_lshl_add_u32 v0, s10, 7, v154
	ds_read_b128 v[98:101], v0 offset:128
	ds_read_b128 v[102:105], v0 offset:192
	s_waitcnt lgkmcnt(9)
	v_alignbit_b32 v122, v123, v122, v151
	v_alignbit_b32 v123, v124, v123, v151
	v_alignbit_b32 v124, v125, v124, v151
	v_alignbit_b32 v125, v177, v125, v151
	s_waitcnt lgkmcnt(6)
	v_alignbit_b32 v134, v135, v134, v151
	v_alignbit_b32 v135, v136, v135, v151
	v_alignbit_b32 v136, v137, v136, v151
	v_alignbit_b32 v137, v178, v137, v151
	s_waitcnt lgkmcnt(0)
	s_cmp_lt_u32 s9, 59
	s_cbranch_scc0 .Lhy_slow_1112
	v_add_u32_e32 v0, s8, v155
	ds_read_b128 v[168:171], v0
	ds_read_b128 v[172:175], v0 offset:64
	s_setprio 1
	v_mfma_f32_16x16x32_bf16 v[62:65], v[134:137], v[110:113], v[62:65]
	v_mfma_f32_16x16x32_bf16 v[58:61], v[122:125], v[110:113], v[58:61]
	v_mfma_f32_16x16x32_bf16 v[54:57], v[118:121], v[110:113], v[54:57]
	v_mfma_f32_16x16x32_bf16 v[50:53], v[106:109], v[110:113], v[50:53]
	v_mfma_f32_16x16x32_bf16 v[62:65], v[142:145], v[114:117], v[62:65]
	v_mfma_f32_16x16x32_bf16 v[58:61], v[138:141], v[114:117], v[58:61]
	v_mfma_f32_16x16x32_bf16 v[54:57], v[134:137], v[114:117], v[54:57]
	v_mfma_f32_16x16x32_bf16 v[50:53], v[122:125], v[114:117], v[50:53]
	v_mfma_f32_16x16x32_bf16 v[78:81], v[134:137], v[126:129], v[78:81]
	v_mfma_f32_16x16x32_bf16 v[74:77], v[122:125], v[126:129], v[74:77]
	v_mfma_f32_16x16x32_bf16 v[70:73], v[118:121], v[126:129], v[70:73]
	v_mfma_f32_16x16x32_bf16 v[66:69], v[106:109], v[126:129], v[66:69]
	v_mfma_f32_16x16x32_bf16 v[78:81], v[142:145], v[130:133], v[78:81]
	v_mfma_f32_16x16x32_bf16 v[74:77], v[138:141], v[130:133], v[74:77]
	v_mfma_f32_16x16x32_bf16 v[70:73], v[134:137], v[130:133], v[70:73]
	v_mfma_f32_16x16x32_bf16 v[66:69], v[122:125], v[130:133], v[66:69]
	v_mfma_f32_16x16x32_bf16 v[46:49], v[134:137], v[98:101], v[46:49]
	v_mfma_f32_16x16x32_bf16 v[42:45], v[122:125], v[98:101], v[42:45]
	v_mfma_f32_16x16x32_bf16 v[38:41], v[118:121], v[98:101], v[38:41]
	v_mfma_f32_16x16x32_bf16 v[34:37], v[106:109], v[98:101], v[34:37]
	v_mfma_f32_16x16x32_bf16 v[46:49], v[142:145], v[102:105], v[46:49]
	v_mfma_f32_16x16x32_bf16 v[42:45], v[138:141], v[102:105], v[42:45]
	v_mfma_f32_16x16x32_bf16 v[38:41], v[134:137], v[102:105], v[38:41]
	v_mfma_f32_16x16x32_bf16 v[34:37], v[122:125], v[102:105], v[34:37]
	s_setprio 0
	s_waitcnt lgkmcnt(0)
	s_setprio 1
	v_mfma_f32_16x16x32_bf16 v[94:97], v[134:137], v[168:171], v[94:97]
	v_mfma_f32_16x16x32_bf16 v[90:93], v[122:125], v[168:171], v[90:93]
	v_mfma_f32_16x16x32_bf16 v[86:89], v[118:121], v[168:171], v[86:89]
	v_mfma_f32_16x16x32_bf16 v[82:85], v[106:109], v[168:171], v[82:85]
	v_mfma_f32_16x16x32_bf16 v[94:97], v[142:145], v[172:175], v[94:97]
	v_mfma_f32_16x16x32_bf16 v[90:93], v[138:141], v[172:175], v[90:93]
	v_mfma_f32_16x16x32_bf16 v[86:89], v[134:137], v[172:175], v[86:89]
	v_mfma_f32_16x16x32_bf16 v[82:85], v[122:125], v[172:175], v[82:85]
	s_setprio 0
	s_add_i32 s9, s9, -1
	s_addk_i32 s8, 0xff80
	s_cmpk_lg_i32 s8, 0xdc80
	s_cbranch_scc1 .LBB0_1112
	s_branch .LBB0_1120
.Lhy_slow_1112:
	s_cmp_gt_u32 s9, 64
	s_cbranch_scc1 .LBB0_1116
	v_add_u32_e32 v0, s8, v155
	ds_read_b128 v[168:171], v0
	ds_read_b128 v[172:175], v0 offset:64
	s_waitcnt lgkmcnt(1)
	s_setprio 1
	v_mfma_f32_16x16x32_bf16 v[94:97], v[134:137], v[168:171], v[94:97]
	v_mfma_f32_16x16x32_bf16 v[90:93], v[122:125], v[168:171], v[90:93]
	v_mfma_f32_16x16x32_bf16 v[86:89], v[118:121], v[168:171], v[86:89]
	v_mfma_f32_16x16x32_bf16 v[82:85], v[106:109], v[168:171], v[82:85]
	s_setprio 0
	s_waitcnt lgkmcnt(0)
	s_setprio 1
	v_mfma_f32_16x16x32_bf16 v[94:97], v[142:145], v[172:175], v[94:97]
	v_mfma_f32_16x16x32_bf16 v[90:93], v[138:141], v[172:175], v[90:93]
	v_mfma_f32_16x16x32_bf16 v[86:89], v[134:137], v[172:175], v[86:89]
	v_mfma_f32_16x16x32_bf16 v[82:85], v[122:125], v[172:175], v[82:85]
	s_setprio 0
	s_add_i32 s10, s9, 2
	s_cmp_gt_u32 s10, 64
	s_cbranch_scc0 .LBB0_1117

; template <int LSEL>
; __device__ __forceinline__ void hy_conv(const bf16_t* Z, const bf16_t* G, f32x4 (&acc)[4][4], int w, int lane) {
;     ...
; #pragma unroll
;     for (int k = 0; k < 4; ++k) {
;       const int js = (q0 + k) * BPT - d;
;       const bool valid = LSEL ? (js >= -1 && js <= NB - 1) : (js >= 0 && js <= NB - 1);
;       if (valid) {
; #pragma unroll
;         for (int mt = 0; mt < 4; ++mt) {
;           acc[k][mt] = __builtin_amdgcn_mfma_f32_16x16x32_bf16(F[3 - mt], bf[k][0], acc[k][mt], 0, 0, 0);
;           acc[k][mt] = __builtin_amdgcn_mfma_f32_16x16x32_bf16(F[5 - mt], bf[k][1], acc[k][mt], 0, 0, 0);
;         }
;       }
;     }
.LBB0_1115:
	s_setprio 1
	v_mfma_f32_16x16x32_bf16 v[62:65], v[134:137], v[110:113], v[62:65]
	v_mfma_f32_16x16x32_bf16 v[58:61], v[122:125], v[110:113], v[58:61]
	v_mfma_f32_16x16x32_bf16 v[54:57], v[118:121], v[110:113], v[54:57]
	v_mfma_f32_16x16x32_bf16 v[50:53], v[106:109], v[110:113], v[50:53]
	v_mfma_f32_16x16x32_bf16 v[62:65], v[142:145], v[114:117], v[62:65]
	v_mfma_f32_16x16x32_bf16 v[58:61], v[138:141], v[114:117], v[58:61]
	v_mfma_f32_16x16x32_bf16 v[54:57], v[134:137], v[114:117], v[54:57]
	v_mfma_f32_16x16x32_bf16 v[50:53], v[122:125], v[114:117], v[50:53]
	s_setprio 0
	s_add_i32 s10, s9, 6
	s_cmp_gt_u32 s10, 64
	s_cbranch_scc1 .LBB0_1111
	s_branch .LBB0_1119

; template <int LSEL>
; __device__ __forceinline__ void hy_conv(const bf16_t* Z, const bf16_t* G, f32x4 (&acc)[4][4], int w, int lane) {
;     ...
; #pragma unroll
;     for (int k = 0; k < 4; ++k) {
;       const int js = (q0 + k) * BPT - d;
;       const bool valid = LSEL ? (js >= -1 && js <= NB - 1) : (js >= 0 && js <= NB - 1);
;       if (valid) {
; #pragma unroll
;         for (int mt = 0; mt < 4; ++mt) {
;           acc[k][mt] = __builtin_amdgcn_mfma_f32_16x16x32_bf16(F[3 - mt], bf[k][0], acc[k][mt], 0, 0, 0);
;           acc[k][mt] = __builtin_amdgcn_mfma_f32_16x16x32_bf16(F[5 - mt], bf[k][1], acc[k][mt], 0, 0, 0);
;         }
;       }
;     }
.LBB0_1117:
	s_setprio 1
	v_mfma_f32_16x16x32_bf16 v[78:81], v[134:137], v[126:129], v[78:81]
	v_mfma_f32_16x16x32_bf16 v[74:77], v[122:125], v[126:129], v[74:77]
	v_mfma_f32_16x16x32_bf16 v[70:73], v[118:121], v[126:129], v[70:73]
	v_mfma_f32_16x16x32_bf16 v[66:69], v[106:109], v[126:129], v[66:69]
	v_mfma_f32_16x16x32_bf16 v[78:81], v[142:145], v[130:133], v[78:81]
	v_mfma_f32_16x16x32_bf16 v[74:77], v[138:141], v[130:133], v[74:77]
	v_mfma_f32_16x16x32_bf16 v[70:73], v[134:137], v[130:133], v[70:73]
	v_mfma_f32_16x16x32_bf16 v[66:69], v[122:125], v[130:133], v[66:69]
	s_setprio 0
	s_add_i32 s10, s9, 4
	s_cmp_gt_u32 s10, 64
	s_cbranch_scc0 .LBB0_1115

; template <int LSEL>
; __device__ __forceinline__ void hy_conv(const bf16_t* Z, const bf16_t* G, f32x4 (&acc)[4][4], int w, int lane) {
;     ...
; #pragma unroll
;     for (int k = 0; k < 4; ++k) {
;       const int js = (q0 + k) * BPT - d;
;       const bool valid = LSEL ? (js >= -1 && js <= NB - 1) : (js >= 0 && js <= NB - 1);
;       if (valid) {
; #pragma unroll
;         for (int mt = 0; mt < 4; ++mt) {
;           acc[k][mt] = __builtin_amdgcn_mfma_f32_16x16x32_bf16(F[3 - mt], bf[k][0], acc[k][mt], 0, 0, 0);
;           acc[k][mt] = __builtin_amdgcn_mfma_f32_16x16x32_bf16(F[5 - mt], bf[k][1], acc[k][mt], 0, 0, 0);
;         }
;       }
;     }
.LBB0_1119:
	s_setprio 1
	v_mfma_f32_16x16x32_bf16 v[46:49], v[134:137], v[98:101], v[46:49]
	v_mfma_f32_16x16x32_bf16 v[42:45], v[122:125], v[98:101], v[42:45]
	v_mfma_f32_16x16x32_bf16 v[38:41], v[118:121], v[98:101], v[38:41]
	v_mfma_f32_16x16x32_bf16 v[34:37], v[106:109], v[98:101], v[34:37]
	v_mfma_f32_16x16x32_bf16 v[46:49], v[142:145], v[102:105], v[46:49]
	v_mfma_f32_16x16x32_bf16 v[42:45], v[138:141], v[102:105], v[42:45]
	v_mfma_f32_16x16x32_bf16 v[38:41], v[134:137], v[102:105], v[38:41]
	v_mfma_f32_16x16x32_bf16 v[34:37], v[122:125], v[102:105], v[34:37]
	s_setprio 0
	s_branch .LBB0_1111

; __device__ __forceinline__ bf16x8 hy_afrag(const bf16_t* gbase, const bool t2, const bool t1, const unsigned sh) {
;   const uint4 lo = *(const uint4*)gbase, hi = *(const uint4*)(gbase + 8);
;   const unsigned x0 = t2 ? lo.z : lo.x, x1 = t2 ? lo.w : lo.y, x2 = t2 ? hi.x : lo.z, x3 = t2 ? hi.y : lo.w,
;                  x4 = t2 ? hi.z : hi.x, x5 = t2 ? hi.w : hi.y;
;   const unsigned y0 = t1 ? x1 : x0, y1 = t1 ? x2 : x1, y2 = t1 ? x3 : x2, y3 = t1 ? x4 : x3, y4 = t1 ? x5 : x4;
;   union { unsigned u[4]; bf16x8 v; } o;
;   o.u[0] = __builtin_amdgcn_alignbit(y1, y0, sh);
;   o.u[1] = __builtin_amdgcn_alignbit(y2, y1, sh);
;   o.u[2] = __builtin_amdgcn_alignbit(y3, y2, sh);
;   o.u[3] = __builtin_amdgcn_alignbit(y4, y3, sh);
;   return o.v;
; }
; template <int LSEL>
; __device__ __forceinline__ void hy_conv(const bf16_t* Z, const bf16_t* G, f32x4 (&acc)[4][4], int w, int lane) {
;     ...
;   for (int d = i_lo - (NB - 1); d <= i_hi; ++d) {
;     bf16x8 bf[4][2];
; #pragma unroll
;     for (int k = 0; k < 4; ++k) {
;       int js = (q0 + k) * BPT - d;
;       js = min(max(js, LSEL ? -1 : 0), NB - 1);
;       const bf16_t* bp = Z + zb + 64 * js;
;       bf[k][0] = *(const bf16x8*)bp;
;       bf[k][1] = *(const bf16x8*)(bp + 32);
;     }
;     const bf16_t* gb = G + (L - 64 * d + 8 * quad - r - s);
;     bf16x8 F[6];
; #pragma unroll
;     for (int u = 0; u < 6; ++u) F[u] = hy_afrag(gb + 16 * (u - 3), t2, t1, sh);
; #pragma unroll
;     for (int k = 0; k < 4; ++k) {
;       const int js = (q0 + k) * BPT - d;
;       const bool valid = LSEL ? (js >= -1 && js <= NB - 1) : (js >= 0 && js <= NB - 1);
;       if (valid) {
; #pragma unroll
;         for (int mt = 0; mt < 4; ++mt) {
;           acc[k][mt] = __builtin_amdgcn_mfma_f32_16x16x32_bf16(F[3 - mt], bf[k][0], acc[k][mt], 0, 0, 0);
;           acc[k][mt] = __builtin_amdgcn_mfma_f32_16x16x32_bf16(F[5 - mt], bf[k][1], acc[k][mt], 0, 0, 0);
;         }
;       }
;     }
;   }
.LBB0_1205:
	v_add_u32_e32 v0, s9, v176
	v_mov_b32_e32 v138, v106
	v_mov_b32_e32 v139, v107
	v_mov_b32_e32 v140, v108
	v_mov_b32_e32 v141, v109
	v_mov_b32_e32 v142, v118
	v_mov_b32_e32 v143, v119
	v_mov_b32_e32 v144, v120
	v_mov_b32_e32 v145, v121
	ds_read2_b32 v[106:107], v0 offset1:1
	ds_read2_b32 v[108:109], v0 offset0:2 offset1:3
	ds_read_b32 v2, v0 offset:16
	ds_read2_b32 v[118:119], v0 offset0:8 offset1:9
	ds_read2_b32 v[120:121], v0 offset0:10 offset1:11
	ds_read_b32 v3, v0 offset:48
	ds_read2_b32 v[122:123], v0 offset0:16 offset1:17
	ds_read2_b32 v[124:125], v0 offset0:18 offset1:19
	ds_read_b32 v177, v0 offset:80
	ds_read2_b32 v[134:135], v0 offset0:24 offset1:25
	ds_read2_b32 v[136:137], v0 offset0:26 offset1:27
	ds_read_b32 v178, v0 offset:112
	s_add_i32 s10, s8, 1
	v_med3_i32 v0, s10, -1, 63
	v_lshl_add_u32 v0, v0, 7, v154
	s_add_i32 s10, s8, 3
	ds_read_b128 v[126:129], v0 offset:128
	ds_read_b128 v[130:133], v0 offset:192
	s_waitcnt lgkmcnt(11)
	v_alignbit_b32 v106, v107, v106, v151
	v_alignbit_b32 v107, v108, v107, v151
	v_alignbit_b32 v108, v109, v108, v151
	v_alignbit_b32 v109, v2, v109, v151
	v_med3_i32 v0, s10, -1, 63
	s_add_i32 s10, s8, 5
	v_lshl_add_u32 v0, v0, 7, v154
	s_min_i32 s10, s10, 63
	ds_read_b128 v[110:113], v0 offset:128
	ds_read_b128 v[114:117], v0 offset:192
	s_waitcnt lgkmcnt(10)
	v_alignbit_b32 v118, v119, v118, v151
	v_alignbit_b32 v119, v120, v119, v151
	v_alignbit_b32 v120, v121, v120, v151
	v_alignbit_b32 v121, v3, v121, v151
	v_lshl_add_u32 v0, s10, 7, v154
	ds_read_b128 v[98:101], v0 offset:128
	ds_read_b128 v[102:105], v0 offset:192
	s_waitcnt lgkmcnt(9)
	v_alignbit_b32 v122, v123, v122, v151
	v_alignbit_b32 v123, v124, v123, v151
	v_alignbit_b32 v124, v125, v124, v151
	v_alignbit_b32 v125, v177, v125, v151
	s_waitcnt lgkmcnt(6)
	v_alignbit_b32 v134, v135, v134, v151
	v_alignbit_b32 v135, v136, v135, v151
	v_alignbit_b32 v136, v137, v136, v151
	v_alignbit_b32 v137, v178, v137, v151
	s_waitcnt lgkmcnt(0)
	s_cmp_lt_u32 s8, 59
	s_cbranch_scc0 .Lhy_slow_1205
	v_add_u32_e32 v0, s9, v155
	ds_read_b128 v[168:171], v0
	ds_read_b128 v[172:175], v0 offset:64
	s_setprio 1
	v_mfma_f32_16x16x32_bf16 v[34:37], v[134:137], v[110:113], v[34:37]
	v_mfma_f32_16x16x32_bf16 v[30:33], v[122:125], v[110:113], v[30:33]
	v_mfma_f32_16x16x32_bf16 v[26:29], v[118:121], v[110:113], v[26:29]
	v_mfma_f32_16x16x32_bf16 v[22:25], v[106:109], v[110:113], v[22:25]
	v_mfma_f32_16x16x32_bf16 v[34:37], v[142:145], v[114:117], v[34:37]
	v_mfma_f32_16x16x32_bf16 v[30:33], v[138:141], v[114:117], v[30:33]
	v_mfma_f32_16x16x32_bf16 v[26:29], v[134:137], v[114:117], v[26:29]
	v_mfma_f32_16x16x32_bf16 v[22:25], v[122:125], v[114:117], v[22:25]
	v_mfma_f32_16x16x32_bf16 v[54:57], v[134:137], v[126:129], v[54:57]
	v_mfma_f32_16x16x32_bf16 v[50:53], v[122:125], v[126:129], v[50:53]
	v_mfma_f32_16x16x32_bf16 v[46:49], v[118:121], v[126:129], v[46:49]
	v_mfma_f32_16x16x32_bf16 v[38:41], v[106:109], v[126:129], v[38:41]
	v_mfma_f32_16x16x32_bf16 v[54:57], v[142:145], v[130:133], v[54:57]
	v_mfma_f32_16x16x32_bf16 v[50:53], v[138:141], v[130:133], v[50:53]
	v_mfma_f32_16x16x32_bf16 v[46:49], v[134:137], v[130:133], v[46:49]
	v_mfma_f32_16x16x32_bf16 v[38:41], v[122:125], v[130:133], v[38:41]
	v_mfma_f32_16x16x32_bf16 v[18:21], v[134:137], v[98:101], v[18:21]
	v_mfma_f32_16x16x32_bf16 v[14:17], v[122:125], v[98:101], v[14:17]
	v_mfma_f32_16x16x32_bf16 v[10:13], v[118:121], v[98:101], v[10:13]
	v_mfma_f32_16x16x32_bf16 v[6:9], v[106:109], v[98:101], v[6:9]
	v_mfma_f32_16x16x32_bf16 v[18:21], v[142:145], v[102:105], v[18:21]
	v_mfma_f32_16x16x32_bf16 v[14:17], v[138:141], v[102:105], v[14:17]
	v_mfma_f32_16x16x32_bf16 v[10:13], v[134:137], v[102:105], v[10:13]
	v_mfma_f32_16x16x32_bf16 v[6:9], v[122:125], v[102:105], v[6:9]
	s_setprio 0
	s_waitcnt lgkmcnt(0)
	s_setprio 1
	v_mfma_f32_16x16x32_bf16 v[74:77], v[134:137], v[168:171], v[74:77]
	v_mfma_f32_16x16x32_bf16 v[66:69], v[122:125], v[168:171], v[66:69]
	v_mfma_f32_16x16x32_bf16 v[62:65], v[118:121], v[168:171], v[62:65]
	v_mfma_f32_16x16x32_bf16 v[58:61], v[106:109], v[168:171], v[58:61]
	v_mfma_f32_16x16x32_bf16 v[74:77], v[142:145], v[172:175], v[74:77]
	v_mfma_f32_16x16x32_bf16 v[66:69], v[138:141], v[172:175], v[66:69]
	v_mfma_f32_16x16x32_bf16 v[62:65], v[134:137], v[172:175], v[62:65]
	v_mfma_f32_16x16x32_bf16 v[58:61], v[122:125], v[172:175], v[58:61]
	s_setprio 0
	s_add_i32 s8, s8, -1
	s_addk_i32 s9, 0xff80
	s_cmpk_lg_i32 s9, 0xdc80
	s_cbranch_scc1 .LBB0_1205
	s_branch .LBB0_1213
.Lhy_slow_1205:
	s_cmp_gt_u32 s8, 64
	s_cbranch_scc1 .LBB0_1209
	v_add_u32_e32 v0, s9, v155
	ds_read_b128 v[168:171], v0
	ds_read_b128 v[172:175], v0 offset:64
	s_waitcnt lgkmcnt(1)
	s_setprio 1
	v_mfma_f32_16x16x32_bf16 v[74:77], v[134:137], v[168:171], v[74:77]
	v_mfma_f32_16x16x32_bf16 v[66:69], v[122:125], v[168:171], v[66:69]
	v_mfma_f32_16x16x32_bf16 v[62:65], v[118:121], v[168:171], v[62:65]
	v_mfma_f32_16x16x32_bf16 v[58:61], v[106:109], v[168:171], v[58:61]
	s_setprio 0
	s_waitcnt lgkmcnt(0)
	s_setprio 1
	v_mfma_f32_16x16x32_bf16 v[74:77], v[142:145], v[172:175], v[74:77]
	v_mfma_f32_16x16x32_bf16 v[66:69], v[138:141], v[172:175], v[66:69]
	v_mfma_f32_16x16x32_bf16 v[62:65], v[134:137], v[172:175], v[62:65]
	v_mfma_f32_16x16x32_bf16 v[58:61], v[122:125], v[172:175], v[58:61]
	s_setprio 0
	s_add_i32 s10, s8, 2
	s_cmp_gt_u32 s10, 64
	s_cbranch_scc0 .LBB0_1210

; template <int LSEL>
; __device__ __forceinline__ void hy_conv(const bf16_t* Z, const bf16_t* G, f32x4 (&acc)[4][4], int w, int lane) {
;     ...
; #pragma unroll
;     for (int k = 0; k < 4; ++k) {
;       const int js = (q0 + k) * BPT - d;
;       const bool valid = LSEL ? (js >= -1 && js <= NB - 1) : (js >= 0 && js <= NB - 1);
;       if (valid) {
; #pragma unroll
;         for (int mt = 0; mt < 4; ++mt) {
;           acc[k][mt] = __builtin_amdgcn_mfma_f32_16x16x32_bf16(F[3 - mt], bf[k][0], acc[k][mt], 0, 0, 0);
;           acc[k][mt] = __builtin_amdgcn_mfma_f32_16x16x32_bf16(F[5 - mt], bf[k][1], acc[k][mt], 0, 0, 0);
;         }
;       }
;     }
.LBB0_1208:
	s_setprio 1
	v_mfma_f32_16x16x32_bf16 v[34:37], v[134:137], v[110:113], v[34:37]
	v_mfma_f32_16x16x32_bf16 v[30:33], v[122:125], v[110:113], v[30:33]
	v_mfma_f32_16x16x32_bf16 v[26:29], v[118:121], v[110:113], v[26:29]
	v_mfma_f32_16x16x32_bf16 v[22:25], v[106:109], v[110:113], v[22:25]
	v_mfma_f32_16x16x32_bf16 v[34:37], v[142:145], v[114:117], v[34:37]
	v_mfma_f32_16x16x32_bf16 v[30:33], v[138:141], v[114:117], v[30:33]
	v_mfma_f32_16x16x32_bf16 v[26:29], v[134:137], v[114:117], v[26:29]
	v_mfma_f32_16x16x32_bf16 v[22:25], v[122:125], v[114:117], v[22:25]
	s_setprio 0
	s_add_i32 s10, s8, 6
	s_cmp_gt_u32 s10, 64
	s_cbranch_scc1 .LBB0_1204
	s_branch .LBB0_1212

; template <int LSEL>
; __device__ __forceinline__ void hy_conv(const bf16_t* Z, const bf16_t* G, f32x4 (&acc)[4][4], int w, int lane) {
;     ...
; #pragma unroll
;     for (int k = 0; k < 4; ++k) {
;       const int js = (q0 + k) * BPT - d;
;       const bool valid = LSEL ? (js >= -1 && js <= NB - 1) : (js >= 0 && js <= NB - 1);
;       if (valid) {
; #pragma unroll
;         for (int mt = 0; mt < 4; ++mt) {
;           acc[k][mt] = __builtin_amdgcn_mfma_f32_16x16x32_bf16(F[3 - mt], bf[k][0], acc[k][mt], 0, 0, 0);
;           acc[k][mt] = __builtin_amdgcn_mfma_f32_16x16x32_bf16(F[5 - mt], bf[k][1], acc[k][mt], 0, 0, 0);
;         }
;       }
;     }
.LBB0_1210:
	s_setprio 1
	v_mfma_f32_16x16x32_bf16 v[54:57], v[134:137], v[126:129], v[54:57]
	v_mfma_f32_16x16x32_bf16 v[50:53], v[122:125], v[126:129], v[50:53]
	v_mfma_f32_16x16x32_bf16 v[46:49], v[118:121], v[126:129], v[46:49]
	v_mfma_f32_16x16x32_bf16 v[38:41], v[106:109], v[126:129], v[38:41]
	v_mfma_f32_16x16x32_bf16 v[54:57], v[142:145], v[130:133], v[54:57]
	v_mfma_f32_16x16x32_bf16 v[50:53], v[138:141], v[130:133], v[50:53]
	v_mfma_f32_16x16x32_bf16 v[46:49], v[134:137], v[130:133], v[46:49]
	v_mfma_f32_16x16x32_bf16 v[38:41], v[122:125], v[130:133], v[38:41]
	s_setprio 0
	s_add_i32 s10, s8, 4
	s_cmp_gt_u32 s10, 64
	s_cbranch_scc0 .LBB0_1208

; template <int LSEL>
; __device__ __forceinline__ void hy_conv(const bf16_t* Z, const bf16_t* G, f32x4 (&acc)[4][4], int w, int lane) {
;     ...
; #pragma unroll
;     for (int k = 0; k < 4; ++k) {
;       const int js = (q0 + k) * BPT - d;
;       const bool valid = LSEL ? (js >= -1 && js <= NB - 1) : (js >= 0 && js <= NB - 1);
;       if (valid) {
; #pragma unroll
;         for (int mt = 0; mt < 4; ++mt) {
;           acc[k][mt] = __builtin_amdgcn_mfma_f32_16x16x32_bf16(F[3 - mt], bf[k][0], acc[k][mt], 0, 0, 0);
;           acc[k][mt] = __builtin_amdgcn_mfma_f32_16x16x32_bf16(F[5 - mt], bf[k][1], acc[k][mt], 0, 0, 0);
;         }
;       }
;     }
.LBB0_1212:
	s_setprio 1
	v_mfma_f32_16x16x32_bf16 v[18:21], v[134:137], v[98:101], v[18:21]
	v_mfma_f32_16x16x32_bf16 v[14:17], v[122:125], v[98:101], v[14:17]
	v_mfma_f32_16x16x32_bf16 v[10:13], v[118:121], v[98:101], v[10:13]
	v_mfma_f32_16x16x32_bf16 v[6:9], v[106:109], v[98:101], v[6:9]
	v_mfma_f32_16x16x32_bf16 v[18:21], v[142:145], v[102:105], v[18:21]
	v_mfma_f32_16x16x32_bf16 v[14:17], v[138:141], v[102:105], v[14:17]
	v_mfma_f32_16x16x32_bf16 v[10:13], v[134:137], v[102:105], v[10:13]
	v_mfma_f32_16x16x32_bf16 v[6:9], v[122:125], v[102:105], v[6:9]
	s_setprio 0
	s_branch .LBB0_1204
